# stack13 + IN main loop LDS-DMA addressed as SGPR base + 32-bit lane offset (no per-DMA 64-bit VALU address op)
# speedup vs baseline: 1.0134x; 1.0060x over previous
; #define PG8_STAGE(bufoff, gbase) do { _Pragma("unroll") for (int _i = 0; _i < 2; ++_i) \
;         __builtin_amdgcn_global_load_lds((const unsigned*)((const char*)(gbase) + voffA[_i]), (LAS unsigned*)(lds + (bufoff) + ldsw + _i * 8192), 16, 0, 0); } while (0)
; #define PG8_LDA(dst, b, h) do { _Pragma("unroll") for (int m = 0; m < 4; ++m) _Pragma("unroll") for (int k = 0; k < 2; ++k) dst[m][k] = *(const LAS h16x8*)(lds + PG8_SA(b, h) + aoff + m * 2048 + k * 1024); } while (0)
; #define PG8_LDB(dst, b, h) do { _Pragma("unroll") for (int n = 0; n < 2; ++n) _Pragma("unroll") for (int k = 0; k < 2; ++k) dst[n][k] = *(const LAS h16x8*)(lds + PG8_SB(b, h) + boff + n * 2048 + k * 1024); } while (0)
; #define PG8_LDA1(dst, b) do { if constexpr (!HALFM) PG8_LDA(dst, b, 1); } while (0)
; #define PG8_MMA1(At, B0, B1) do { if constexpr (!HALFM) { PG8_MMA(1, 0, At, B0); PG8_MMA(1, 1, At, B1); } } while (0)
; #define PG8_WAIT_V(n) asm volatile("s_waitcnt vmcnt(" #n ")" ::: "memory")
; #define PG8_WAIT_L(n) asm volatile("s_waitcnt lgkmcnt(" #n ")" ::: "memory")
; #define PG8_BAR __builtin_amdgcn_s_barrier()
; #define PG8_SCHED __builtin_amdgcn_sched_barrier(0)
; template <class Epi, bool ALIGN_EPI, bool SP2, bool BF = false, bool HALFM = false, class Order = StaticOrder>
; __device__ __forceinline__ void gemm_phase(LAS unsigned char* lds, const int tid, const Gemm g, const Order& S, const Epi& E, const bool dry = false) {
;     ...
;             PG8_LDB(B0, 0, 0); PG8_LDB(B1, 0, 1); PG8_SCHED; PG8_LDA(At, 0, 0); PG8_STAGE(PG8_SA(1, 1), a1 + hstep);
;             PG8_WAIT_V(8); PG8_WAIT_L(0); PG8_BAR; PG8_MMA(0, 0, At, B0); PG8_MMA(0, 1, At, B1); PG8_BAR; PG8_SCHED;
;             PG8_LDA1(At, 0); PG8_STAGE(PG8_SB(0, 0), b2); PG8_STAGE(PG8_SB(0, 1), b2 + hstep); PG8_STAGE(PG8_SA(0, 0), a2);
;             PG8_WAIT_V(8); PG8_WAIT_L(0); PG8_BAR; PG8_MMA1(At, B0, B1); PG8_BAR; PG8_SCHED;
;             PG8_LDB(B0, 1, 0); PG8_LDB(B1, 1, 1); PG8_SCHED; PG8_LDA(At, 1, 0); PG8_STAGE(PG8_SA(0, 1), a2 + hstep);
;             PG8_WAIT_V(8); PG8_WAIT_L(0); PG8_BAR; PG8_MMA(0, 0, At, B0); PG8_MMA(0, 1, At, B1); PG8_BAR; PG8_SCHED;
;             PG8_LDA1(At, 1); PG8_STAGE(PG8_SB(1, 0), b3); PG8_STAGE(PG8_SB(1, 1), b3 + hstep); PG8_STAGE(PG8_SA(1, 0), a3);
;             PG8_WAIT_V(8); PG8_WAIT_L(0); PG8_BAR; PG8_MMA1(At, B0, B1); PG8_BAR; PG8_SCHED;
.Lin_peel:
	v_add_u32_e32 v144, s46, v198
	v_add_u32_e32 v160, s49, v198
	ds_read_b128 v[132:135], v144
	ds_read_b128 v[136:139], v144 offset:1024
	ds_read_b128 v[140:143], v144 offset:2048
	ds_read_b128 v[144:147], v144 offset:3072
	ds_read_b128 v[148:151], v160
	ds_read_b128 v[152:155], v160 offset:1024
	ds_read_b128 v[156:159], v160 offset:2048
	ds_read_b128 v[160:163], v160 offset:3072
	s_add_u32 s38, s36, 0xfffc0080
	s_addc_u32 s39, s37, -1
	s_cmp_eq_u32 s21, 12
	s_cselect_b32 s43, s3, s39
	s_cselect_b32 s42, s5, s38
	s_cselect_b32 s39, s8, s19
	s_cselect_b32 s38, s9, s11
	s_nop 0
	s_add_i32 m0, s52, 0xc000
	ds_read_b128 v[170:173], v199
	ds_read_b128 v[174:177], v199 offset:1024
	ds_read_b128 v[178:181], v199 offset:2048
	ds_read_b128 v[182:185], v199 offset:3072
	ds_read_b128 v[186:189], v199 offset:4096
	ds_read_b128 v[190:193], v199 offset:5120
	ds_read_b128 v[200:203], v199 offset:6144
	ds_read_b128 v[204:207], v199 offset:7168
	s_nop 0
	s_nop 0
	s_add_i32 m0, s52, 0xe000
	s_nop 0
	s_nop 0
	s_nop 0
	s_waitcnt lgkmcnt(0)
	s_barrier
	s_waitcnt lgkmcnt(0)
	v_mfma_f32_16x16x32_f16 v[70:73], v[132:135], v[170:173], 0
	v_mfma_f32_16x16x32_f16 v[66:69], v[140:143], v[170:173], 0
	v_mfma_f32_16x16x32_f16 v[50:53], v[132:135], v[178:181], 0
	v_mfma_f32_16x16x32_f16 v[46:49], v[140:143], v[178:181], 0
	v_mfma_f32_16x16x32_f16 v[54:57], v[132:135], v[186:189], 0
	v_mfma_f32_16x16x32_f16 v[42:45], v[140:143], v[186:189], 0
	v_mfma_f32_16x16x32_f16 v[38:41], v[132:135], v[200:203], 0
	v_mfma_f32_16x16x32_f16 v[34:37], v[140:143], v[200:203], 0
	v_mfma_f32_16x16x32_f16 v[70:73], v[136:139], v[174:177], v[70:73]
	v_mfma_f32_16x16x32_f16 v[66:69], v[144:147], v[174:177], v[66:69]
	v_mfma_f32_16x16x32_f16 v[50:53], v[136:139], v[182:185], v[50:53]
	v_mfma_f32_16x16x32_f16 v[46:49], v[144:147], v[182:185], v[46:49]
	v_mfma_f32_16x16x32_f16 v[54:57], v[136:139], v[190:193], v[54:57]
	v_mfma_f32_16x16x32_f16 v[42:45], v[144:147], v[190:193], v[42:45]
	v_mfma_f32_16x16x32_f16 v[38:41], v[136:139], v[204:207], v[38:41]
	v_mfma_f32_16x16x32_f16 v[34:37], v[144:147], v[204:207], v[34:37]
	v_mfma_f32_16x16x32_f16 v[126:129], v[148:151], v[170:173], 0
	v_mfma_f32_16x16x32_f16 v[122:125], v[156:159], v[170:173], 0
	v_mfma_f32_16x16x32_f16 v[118:121], v[148:151], v[178:181], 0
	v_mfma_f32_16x16x32_f16 v[114:117], v[156:159], v[178:181], 0
	v_mfma_f32_16x16x32_f16 v[110:113], v[148:151], v[186:189], 0
	v_mfma_f32_16x16x32_f16 v[106:109], v[156:159], v[186:189], 0
	v_mfma_f32_16x16x32_f16 v[102:105], v[148:151], v[200:203], 0
	v_mfma_f32_16x16x32_f16 v[98:101], v[156:159], v[200:203], 0
	v_mfma_f32_16x16x32_f16 v[126:129], v[152:155], v[174:177], v[126:129]
	v_mfma_f32_16x16x32_f16 v[122:125], v[160:163], v[174:177], v[122:125]
	v_mfma_f32_16x16x32_f16 v[118:121], v[152:155], v[182:185], v[118:121]
	v_mfma_f32_16x16x32_f16 v[114:117], v[160:163], v[182:185], v[114:117]
	v_mfma_f32_16x16x32_f16 v[110:113], v[152:155], v[190:193], v[110:113]
	v_mfma_f32_16x16x32_f16 v[106:109], v[160:163], v[190:193], v[106:109]
	v_mfma_f32_16x16x32_f16 v[102:105], v[152:155], v[204:207], v[102:105]
	v_mfma_f32_16x16x32_f16 v[98:101], v[160:163], v[204:207], v[98:101]
	s_barrier
	s_mov_b32 m0, s47
	s_nop 0
	s_add_u32 vcc_lo, s38, 0x40000
	ds_read_b128 v[170:173], v199 offset:16384
	ds_read_b128 v[174:177], v199 offset:17408
	ds_read_b128 v[178:181], v199 offset:18432
	ds_read_b128 v[182:185], v199 offset:19456
	ds_read_b128 v[186:189], v199 offset:20480
	ds_read_b128 v[190:193], v199 offset:21504
	ds_read_b128 v[200:203], v199 offset:22528
	ds_read_b128 v[204:207], v199 offset:23552
	global_load_lds_dwordx4 v0, s[38:39]
	s_nop 0
	s_mov_b32 m0, s48
	s_addc_u32 vcc_hi, s39, 0
	global_load_lds_dwordx4 v164, s[38:39]
	s_nop 0
	s_mov_b32 m0, s50
	s_nop 0
	global_load_lds_dwordx4 v0, vcc
	s_nop 0
	s_mov_b32 m0, s51
	s_nop 0
	global_load_lds_dwordx4 v164, vcc
	s_nop 0
	s_mov_b32 m0, s52
	s_nop 0
	global_load_lds_dwordx4 v0, s[42:43]
	s_mov_b32 m0, s53
	s_nop 0
	global_load_lds_dwordx4 v164, s[42:43]
	s_nop 0
	s_waitcnt lgkmcnt(0)
	s_barrier
; #define PG8_STAGE(bufoff, gbase) do { _Pragma("unroll") for (int _i = 0; _i < 2; ++_i) \
;         __builtin_amdgcn_global_load_lds((const unsigned*)((const char*)(gbase) + voffA[_i]), (LAS unsigned*)(lds + (bufoff) + ldsw + _i * 8192), 16, 0, 0); } while (0)
; #define PG8_LDA(dst, b, h) do { _Pragma("unroll") for (int m = 0; m < 4; ++m) _Pragma("unroll") for (int k = 0; k < 2; ++k) dst[m][k] = *(const LAS h16x8*)(lds + PG8_SA(b, h) + aoff + m * 2048 + k * 1024); } while (0)
; #define PG8_LDB(dst, b, h) do { _Pragma("unroll") for (int n = 0; n < 2; ++n) _Pragma("unroll") for (int k = 0; k < 2; ++k) dst[n][k] = *(const LAS h16x8*)(lds + PG8_SB(b, h) + boff + n * 2048 + k * 1024); } while (0)
; #define PG8_LDA1(dst, b) do { if constexpr (!HALFM) PG8_LDA(dst, b, 1); } while (0)
; #define PG8_MMA1(At, B0, B1) do { if constexpr (!HALFM) { PG8_MMA(1, 0, At, B0); PG8_MMA(1, 1, At, B1); } } while (0)
; #define PG8_WAIT_V(n) asm volatile("s_waitcnt vmcnt(" #n ")" ::: "memory")
; #define PG8_WAIT_L(n) asm volatile("s_waitcnt lgkmcnt(" #n ")" ::: "memory")
; #define PG8_BAR __builtin_amdgcn_s_barrier()
; #define PG8_SCHED __builtin_amdgcn_sched_barrier(0)
; template <class Epi, bool ALIGN_EPI, bool SP2, bool BF = false, bool HALFM = false, class Order = StaticOrder>
; __device__ __forceinline__ void gemm_phase(LAS unsigned char* lds, const int tid, const Gemm g, const Order& S, const Epi& E, const bool dry = false) {
;     ...
;             PG8_LDB(B0, 0, 0); PG8_LDB(B1, 0, 1); PG8_SCHED; PG8_LDA(At, 0, 0); PG8_STAGE(PG8_SA(1, 1), a1 + hstep);
;             PG8_WAIT_V(8); PG8_WAIT_L(0); PG8_BAR; PG8_MMA(0, 0, At, B0); PG8_MMA(0, 1, At, B1); PG8_BAR; PG8_SCHED;
;             PG8_LDA1(At, 0); PG8_STAGE(PG8_SB(0, 0), b2); PG8_STAGE(PG8_SB(0, 1), b2 + hstep); PG8_STAGE(PG8_SA(0, 0), a2);
;             PG8_WAIT_V(8); PG8_WAIT_L(0); PG8_BAR; PG8_MMA1(At, B0, B1); PG8_BAR; PG8_SCHED;
;             PG8_LDB(B0, 1, 0); PG8_LDB(B1, 1, 1); PG8_SCHED; PG8_LDA(At, 1, 0); PG8_STAGE(PG8_SA(0, 1), a2 + hstep);
;             PG8_WAIT_V(8); PG8_WAIT_L(0); PG8_BAR; PG8_MMA(0, 0, At, B0); PG8_MMA(0, 1, At, B1); PG8_BAR; PG8_SCHED;
;             PG8_LDA1(At, 1); PG8_STAGE(PG8_SB(1, 0), b3); PG8_STAGE(PG8_SB(1, 1), b3 + hstep); PG8_STAGE(PG8_SA(1, 0), a3);
;             PG8_WAIT_V(8); PG8_WAIT_L(0); PG8_BAR; PG8_MMA1(At, B0, B1); PG8_BAR; PG8_SCHED;
	s_waitcnt lgkmcnt(0)
	v_mfma_f32_16x16x32_f16 v[30:33], v[132:135], v[170:173], 0
	v_mfma_f32_16x16x32_f16 v[26:29], v[140:143], v[170:173], 0
	v_mfma_f32_16x16x32_f16 v[22:25], v[132:135], v[178:181], 0
	v_mfma_f32_16x16x32_f16 v[18:21], v[140:143], v[178:181], 0
	v_mfma_f32_16x16x32_f16 v[14:17], v[132:135], v[186:189], 0
	v_mfma_f32_16x16x32_f16 v[10:13], v[140:143], v[186:189], 0
	v_mfma_f32_16x16x32_f16 v[6:9], v[132:135], v[200:203], 0
	v_mfma_f32_16x16x32_f16 v[2:5], v[140:143], v[200:203], 0
	v_mfma_f32_16x16x32_f16 v[30:33], v[136:139], v[174:177], v[30:33]
	v_mfma_f32_16x16x32_f16 v[26:29], v[144:147], v[174:177], v[26:29]
	v_mfma_f32_16x16x32_f16 v[22:25], v[136:139], v[182:185], v[22:25]
	v_mfma_f32_16x16x32_f16 v[18:21], v[144:147], v[182:185], v[18:21]
	v_mfma_f32_16x16x32_f16 v[14:17], v[136:139], v[190:193], v[14:17]
	v_mfma_f32_16x16x32_f16 v[10:13], v[144:147], v[190:193], v[10:13]
	v_mfma_f32_16x16x32_f16 v[6:9], v[136:139], v[204:207], v[6:9]
	v_mfma_f32_16x16x32_f16 v[2:5], v[144:147], v[204:207], v[2:5]
	v_mfma_f32_16x16x32_f16 v[94:97], v[148:151], v[170:173], 0
	v_mfma_f32_16x16x32_f16 v[90:93], v[156:159], v[170:173], 0
	v_mfma_f32_16x16x32_f16 v[86:89], v[148:151], v[178:181], 0
	v_mfma_f32_16x16x32_f16 v[82:85], v[156:159], v[178:181], 0
	v_mfma_f32_16x16x32_f16 v[78:81], v[148:151], v[186:189], 0
	v_mfma_f32_16x16x32_f16 v[74:77], v[156:159], v[186:189], 0
	v_mfma_f32_16x16x32_f16 v[62:65], v[148:151], v[200:203], 0
	v_mfma_f32_16x16x32_f16 v[58:61], v[156:159], v[200:203], 0
	v_mfma_f32_16x16x32_f16 v[94:97], v[152:155], v[174:177], v[94:97]
	v_mfma_f32_16x16x32_f16 v[90:93], v[160:163], v[174:177], v[90:93]
	v_mfma_f32_16x16x32_f16 v[86:89], v[152:155], v[182:185], v[86:89]
	v_mfma_f32_16x16x32_f16 v[82:85], v[160:163], v[182:185], v[82:85]
	v_mfma_f32_16x16x32_f16 v[78:81], v[152:155], v[190:193], v[78:81]
	v_mfma_f32_16x16x32_f16 v[74:77], v[160:163], v[190:193], v[74:77]
	v_mfma_f32_16x16x32_f16 v[62:65], v[152:155], v[204:207], v[62:65]
	v_mfma_f32_16x16x32_f16 v[58:61], v[160:163], v[204:207], v[58:61]
	s_barrier
	v_add_u32_e32 v144, s79, v198
	v_add_u32_e32 v160, s84, v198
	ds_read_b128 v[132:135], v144
	ds_read_b128 v[136:139], v144 offset:1024
	ds_read_b128 v[140:143], v144 offset:2048
	ds_read_b128 v[144:147], v144 offset:3072
	ds_read_b128 v[148:151], v160
	ds_read_b128 v[152:155], v160 offset:1024
	ds_read_b128 v[156:159], v160 offset:2048
	ds_read_b128 v[160:163], v160 offset:3072
	s_add_u32 s42, s42, 0x40000
	s_addc_u32 s43, s43, 0
	s_mov_b32 m0, s54
	s_nop 0
	ds_read_b128 v[170:173], v199 offset:32768
	ds_read_b128 v[174:177], v199 offset:33792
	ds_read_b128 v[178:181], v199 offset:34816
	ds_read_b128 v[182:185], v199 offset:35840
	ds_read_b128 v[186:189], v199 offset:36864
	ds_read_b128 v[190:193], v199 offset:37888
	ds_read_b128 v[200:203], v199 offset:38912
	ds_read_b128 v[204:207], v199 offset:39936
	global_load_lds_dwordx4 v0, s[42:43]
	s_nop 0
	s_mov_b32 m0, s55
	s_nop 0
	global_load_lds_dwordx4 v164, s[42:43]
	s_nop 0
	s_waitcnt lgkmcnt(0)
	s_barrier
	s_waitcnt lgkmcnt(0)
	v_mfma_f32_16x16x32_f16 v[70:73], v[132:135], v[170:173], v[70:73]
	v_mfma_f32_16x16x32_f16 v[66:69], v[140:143], v[170:173], v[66:69]
	v_mfma_f32_16x16x32_f16 v[50:53], v[132:135], v[178:181], v[50:53]
	v_mfma_f32_16x16x32_f16 v[46:49], v[140:143], v[178:181], v[46:49]
	v_mfma_f32_16x16x32_f16 v[54:57], v[132:135], v[186:189], v[54:57]
	v_mfma_f32_16x16x32_f16 v[42:45], v[140:143], v[186:189], v[42:45]
	v_mfma_f32_16x16x32_f16 v[38:41], v[132:135], v[200:203], v[38:41]
	v_mfma_f32_16x16x32_f16 v[34:37], v[140:143], v[200:203], v[34:37]
	v_mfma_f32_16x16x32_f16 v[70:73], v[136:139], v[174:177], v[70:73]
	v_mfma_f32_16x16x32_f16 v[66:69], v[144:147], v[174:177], v[66:69]
	v_mfma_f32_16x16x32_f16 v[50:53], v[136:139], v[182:185], v[50:53]
	v_mfma_f32_16x16x32_f16 v[46:49], v[144:147], v[182:185], v[46:49]
	v_mfma_f32_16x16x32_f16 v[54:57], v[136:139], v[190:193], v[54:57]
	v_mfma_f32_16x16x32_f16 v[42:45], v[144:147], v[190:193], v[42:45]
	v_mfma_f32_16x16x32_f16 v[38:41], v[136:139], v[204:207], v[38:41]
	v_mfma_f32_16x16x32_f16 v[34:37], v[144:147], v[204:207], v[34:37]
	v_mfma_f32_16x16x32_f16 v[126:129], v[148:151], v[170:173], v[126:129]
	v_mfma_f32_16x16x32_f16 v[122:125], v[156:159], v[170:173], v[122:125]
	v_mfma_f32_16x16x32_f16 v[118:121], v[148:151], v[178:181], v[118:121]
	v_mfma_f32_16x16x32_f16 v[114:117], v[156:159], v[178:181], v[114:117]
	v_mfma_f32_16x16x32_f16 v[110:113], v[148:151], v[186:189], v[110:113]
	v_mfma_f32_16x16x32_f16 v[106:109], v[156:159], v[186:189], v[106:109]
	v_mfma_f32_16x16x32_f16 v[102:105], v[148:151], v[200:203], v[102:105]
	v_mfma_f32_16x16x32_f16 v[98:101], v[156:159], v[200:203], v[98:101]
	v_mfma_f32_16x16x32_f16 v[126:129], v[152:155], v[174:177], v[126:129]
	v_mfma_f32_16x16x32_f16 v[122:125], v[160:163], v[174:177], v[122:125]
	v_mfma_f32_16x16x32_f16 v[118:121], v[152:155], v[182:185], v[118:121]
	v_mfma_f32_16x16x32_f16 v[114:117], v[160:163], v[182:185], v[114:117]
	v_mfma_f32_16x16x32_f16 v[110:113], v[152:155], v[190:193], v[110:113]
	v_mfma_f32_16x16x32_f16 v[106:109], v[160:163], v[190:193], v[106:109]
	v_mfma_f32_16x16x32_f16 v[102:105], v[152:155], v[204:207], v[102:105]
	v_mfma_f32_16x16x32_f16 v[98:101], v[160:163], v[204:207], v[98:101]
	s_barrier
	s_branch .Lin_seg4

; #define PG8_STAGE(bufoff, gbase) do { _Pragma("unroll") for (int _i = 0; _i < 2; ++_i) \
;         __builtin_amdgcn_global_load_lds((const unsigned*)((const char*)(gbase) + voffA[_i]), (LAS unsigned*)(lds + (bufoff) + ldsw + _i * 8192), 16, 0, 0); } while (0)
; #define PG8_LDA(dst, b, h) do { _Pragma("unroll") for (int m = 0; m < 4; ++m) _Pragma("unroll") for (int k = 0; k < 2; ++k) dst[m][k] = *(const LAS h16x8*)(lds + PG8_SA(b, h) + aoff + m * 2048 + k * 1024); } while (0)
; #define PG8_LDB(dst, b, h) do { _Pragma("unroll") for (int n = 0; n < 2; ++n) _Pragma("unroll") for (int k = 0; k < 2; ++k) dst[n][k] = *(const LAS h16x8*)(lds + PG8_SB(b, h) + boff + n * 2048 + k * 1024); } while (0)
; #define PG8_LDA1(dst, b) do { if constexpr (!HALFM) PG8_LDA(dst, b, 1); } while (0)
; #define PG8_MMA1(At, B0, B1) do { if constexpr (!HALFM) { PG8_MMA(1, 0, At, B0); PG8_MMA(1, 1, At, B1); } } while (0)
; #define PG8_WAIT_V(n) asm volatile("s_waitcnt vmcnt(" #n ")" ::: "memory")
; #define PG8_WAIT_L(n) asm volatile("s_waitcnt lgkmcnt(" #n ")" ::: "memory")
; #define PG8_BAR __builtin_amdgcn_s_barrier()
; #define PG8_SCHED __builtin_amdgcn_sched_barrier(0)
; template <class Epi, bool ALIGN_EPI, bool SP2, bool BF = false, bool HALFM = false, class Order = StaticOrder>
; __device__ __forceinline__ void gemm_phase(LAS unsigned char* lds, const int tid, const Gemm g, const Order& S, const Epi& E, const bool dry = false) {
;     ...
;             PG8_LDB(B0, 0, 0); PG8_LDB(B1, 0, 1); PG8_SCHED; PG8_LDA(At, 0, 0); PG8_STAGE(PG8_SA(1, 1), a1 + hstep);
;             PG8_WAIT_V(8); PG8_WAIT_L(0); PG8_BAR; PG8_MMA(0, 0, At, B0); PG8_MMA(0, 1, At, B1); PG8_BAR; PG8_SCHED;
;             PG8_LDA1(At, 0); PG8_STAGE(PG8_SB(0, 0), b2); PG8_STAGE(PG8_SB(0, 1), b2 + hstep); PG8_STAGE(PG8_SA(0, 0), a2);
;             PG8_WAIT_V(8); PG8_WAIT_L(0); PG8_BAR; PG8_MMA1(At, B0, B1); PG8_BAR; PG8_SCHED;
;             PG8_LDB(B0, 1, 0); PG8_LDB(B1, 1, 1); PG8_SCHED; PG8_LDA(At, 1, 0); PG8_STAGE(PG8_SA(0, 1), a2 + hstep);
;             PG8_WAIT_V(8); PG8_WAIT_L(0); PG8_BAR; PG8_MMA(0, 0, At, B0); PG8_MMA(0, 1, At, B1); PG8_BAR; PG8_SCHED;
;             PG8_LDA1(At, 1); PG8_STAGE(PG8_SB(1, 0), b3); PG8_STAGE(PG8_SB(1, 1), b3 + hstep); PG8_STAGE(PG8_SA(1, 0), a3);
;             PG8_WAIT_V(8); PG8_WAIT_L(0); PG8_BAR; PG8_MMA1(At, B0, B1); PG8_BAR; PG8_SCHED;
.LBB0_561:
	v_add_u32_e32 v144, s46, v198
	v_add_u32_e32 v160, s49, v198
	ds_read_b128 v[132:135], v144
	ds_read_b128 v[136:139], v144 offset:1024
	ds_read_b128 v[140:143], v144 offset:2048
	ds_read_b128 v[144:147], v144 offset:3072
	ds_read_b128 v[148:151], v160
	ds_read_b128 v[152:155], v160 offset:1024
	ds_read_b128 v[156:159], v160 offset:2048
	ds_read_b128 v[160:163], v160 offset:3072
	s_add_u32 s38, s36, 0xfffc0080
	s_addc_u32 s39, s37, -1
	s_cmp_eq_u32 s21, 12
	s_cselect_b32 s43, s3, s39
	s_cselect_b32 s42, s5, s38
	s_cselect_b32 s39, s8, s19
	s_cselect_b32 s38, s9, s11
	s_nop 0
	s_add_i32 m0, s52, 0xc000
	ds_read_b128 v[170:173], v199
	ds_read_b128 v[174:177], v199 offset:1024
	ds_read_b128 v[178:181], v199 offset:2048
	ds_read_b128 v[182:185], v199 offset:3072
	ds_read_b128 v[186:189], v199 offset:4096
	ds_read_b128 v[190:193], v199 offset:5120
	ds_read_b128 v[200:203], v199 offset:6144
	ds_read_b128 v[204:207], v199 offset:7168
	global_load_lds_dwordx4 v168, s[36:37]
	s_nop 0
	s_add_i32 m0, s52, 0xe000
	s_nop 0
	global_load_lds_dwordx4 v166, s[36:37]
	s_waitcnt vmcnt(8)
	s_waitcnt lgkmcnt(0)
	s_barrier
	s_waitcnt lgkmcnt(0)
	v_mfma_f32_16x16x32_f16 v[70:73], v[132:135], v[170:173], v[70:73]
	v_mfma_f32_16x16x32_f16 v[66:69], v[140:143], v[170:173], v[66:69]
	v_mfma_f32_16x16x32_f16 v[50:53], v[132:135], v[178:181], v[50:53]
	v_mfma_f32_16x16x32_f16 v[46:49], v[140:143], v[178:181], v[46:49]
	v_mfma_f32_16x16x32_f16 v[54:57], v[132:135], v[186:189], v[54:57]
	v_mfma_f32_16x16x32_f16 v[42:45], v[140:143], v[186:189], v[42:45]
	v_mfma_f32_16x16x32_f16 v[38:41], v[132:135], v[200:203], v[38:41]
	v_mfma_f32_16x16x32_f16 v[34:37], v[140:143], v[200:203], v[34:37]
	v_mfma_f32_16x16x32_f16 v[70:73], v[136:139], v[174:177], v[70:73]
	v_mfma_f32_16x16x32_f16 v[66:69], v[144:147], v[174:177], v[66:69]
	v_mfma_f32_16x16x32_f16 v[50:53], v[136:139], v[182:185], v[50:53]
	v_mfma_f32_16x16x32_f16 v[46:49], v[144:147], v[182:185], v[46:49]
	v_mfma_f32_16x16x32_f16 v[54:57], v[136:139], v[190:193], v[54:57]
	v_mfma_f32_16x16x32_f16 v[42:45], v[144:147], v[190:193], v[42:45]
	v_mfma_f32_16x16x32_f16 v[38:41], v[136:139], v[204:207], v[38:41]
	v_mfma_f32_16x16x32_f16 v[34:37], v[144:147], v[204:207], v[34:37]
	v_mfma_f32_16x16x32_f16 v[126:129], v[148:151], v[170:173], v[126:129]
	v_mfma_f32_16x16x32_f16 v[122:125], v[156:159], v[170:173], v[122:125]
	v_mfma_f32_16x16x32_f16 v[118:121], v[148:151], v[178:181], v[118:121]
	v_mfma_f32_16x16x32_f16 v[114:117], v[156:159], v[178:181], v[114:117]
	v_mfma_f32_16x16x32_f16 v[110:113], v[148:151], v[186:189], v[110:113]
	v_mfma_f32_16x16x32_f16 v[106:109], v[156:159], v[186:189], v[106:109]
	v_mfma_f32_16x16x32_f16 v[102:105], v[148:151], v[200:203], v[102:105]
	v_mfma_f32_16x16x32_f16 v[98:101], v[156:159], v[200:203], v[98:101]
	v_mfma_f32_16x16x32_f16 v[126:129], v[152:155], v[174:177], v[126:129]
	v_mfma_f32_16x16x32_f16 v[122:125], v[160:163], v[174:177], v[122:125]
	v_mfma_f32_16x16x32_f16 v[118:121], v[152:155], v[182:185], v[118:121]
	v_mfma_f32_16x16x32_f16 v[114:117], v[160:163], v[182:185], v[114:117]
	v_mfma_f32_16x16x32_f16 v[110:113], v[152:155], v[190:193], v[110:113]
	v_mfma_f32_16x16x32_f16 v[106:109], v[160:163], v[190:193], v[106:109]
	v_mfma_f32_16x16x32_f16 v[102:105], v[152:155], v[204:207], v[102:105]
	v_mfma_f32_16x16x32_f16 v[98:101], v[160:163], v[204:207], v[98:101]
	s_barrier
	s_mov_b32 m0, s47
	s_nop 0
	s_add_u32 vcc_lo, s38, 0x40000
	ds_read_b128 v[170:173], v199 offset:16384
	ds_read_b128 v[174:177], v199 offset:17408
	ds_read_b128 v[178:181], v199 offset:18432
	ds_read_b128 v[182:185], v199 offset:19456
	ds_read_b128 v[186:189], v199 offset:20480
	ds_read_b128 v[190:193], v199 offset:21504
	ds_read_b128 v[200:203], v199 offset:22528
	ds_read_b128 v[204:207], v199 offset:23552
	global_load_lds_dwordx4 v0, s[38:39]
	s_nop 0
	s_mov_b32 m0, s48
	s_addc_u32 vcc_hi, s39, 0
	global_load_lds_dwordx4 v164, s[38:39]
	s_nop 0
	s_mov_b32 m0, s50
	s_nop 0
	global_load_lds_dwordx4 v0, vcc
	s_nop 0
	s_mov_b32 m0, s51
	s_nop 0
	global_load_lds_dwordx4 v164, vcc
	s_nop 0
	s_mov_b32 m0, s52
	s_nop 0
	global_load_lds_dwordx4 v0, s[42:43]
	s_mov_b32 m0, s53
	s_nop 0
	global_load_lds_dwordx4 v164, s[42:43]
	s_waitcnt vmcnt(8)
	s_waitcnt lgkmcnt(0)
	s_barrier
	s_waitcnt lgkmcnt(0)
	v_mfma_f32_16x16x32_f16 v[30:33], v[132:135], v[170:173], v[30:33]
	v_mfma_f32_16x16x32_f16 v[26:29], v[140:143], v[170:173], v[26:29]
	v_mfma_f32_16x16x32_f16 v[22:25], v[132:135], v[178:181], v[22:25]
	v_mfma_f32_16x16x32_f16 v[18:21], v[140:143], v[178:181], v[18:21]
	v_mfma_f32_16x16x32_f16 v[14:17], v[132:135], v[186:189], v[14:17]
	v_mfma_f32_16x16x32_f16 v[10:13], v[140:143], v[186:189], v[10:13]
	v_mfma_f32_16x16x32_f16 v[6:9], v[132:135], v[200:203], v[6:9]
	v_mfma_f32_16x16x32_f16 v[2:5], v[140:143], v[200:203], v[2:5]
	v_mfma_f32_16x16x32_f16 v[30:33], v[136:139], v[174:177], v[30:33]
	v_mfma_f32_16x16x32_f16 v[26:29], v[144:147], v[174:177], v[26:29]
	v_mfma_f32_16x16x32_f16 v[22:25], v[136:139], v[182:185], v[22:25]
	v_mfma_f32_16x16x32_f16 v[18:21], v[144:147], v[182:185], v[18:21]
	v_mfma_f32_16x16x32_f16 v[14:17], v[136:139], v[190:193], v[14:17]
	v_mfma_f32_16x16x32_f16 v[10:13], v[144:147], v[190:193], v[10:13]
	v_mfma_f32_16x16x32_f16 v[6:9], v[136:139], v[204:207], v[6:9]
	v_mfma_f32_16x16x32_f16 v[2:5], v[144:147], v[204:207], v[2:5]
	v_mfma_f32_16x16x32_f16 v[94:97], v[148:151], v[170:173], v[94:97]
	v_mfma_f32_16x16x32_f16 v[90:93], v[156:159], v[170:173], v[90:93]
	v_mfma_f32_16x16x32_f16 v[86:89], v[148:151], v[178:181], v[86:89]
	v_mfma_f32_16x16x32_f16 v[82:85], v[156:159], v[178:181], v[82:85]
	v_mfma_f32_16x16x32_f16 v[78:81], v[148:151], v[186:189], v[78:81]
	v_mfma_f32_16x16x32_f16 v[74:77], v[156:159], v[186:189], v[74:77]
	v_mfma_f32_16x16x32_f16 v[62:65], v[148:151], v[200:203], v[62:65]
	v_mfma_f32_16x16x32_f16 v[58:61], v[156:159], v[200:203], v[58:61]
	v_mfma_f32_16x16x32_f16 v[94:97], v[152:155], v[174:177], v[94:97]
	v_mfma_f32_16x16x32_f16 v[90:93], v[160:163], v[174:177], v[90:93]
	v_mfma_f32_16x16x32_f16 v[86:89], v[152:155], v[182:185], v[86:89]
	v_mfma_f32_16x16x32_f16 v[82:85], v[160:163], v[182:185], v[82:85]
	v_mfma_f32_16x16x32_f16 v[78:81], v[152:155], v[190:193], v[78:81]
	v_mfma_f32_16x16x32_f16 v[74:77], v[160:163], v[190:193], v[74:77]
	v_mfma_f32_16x16x32_f16 v[62:65], v[152:155], v[204:207], v[62:65]
	v_mfma_f32_16x16x32_f16 v[58:61], v[160:163], v[204:207], v[58:61]
	s_barrier
; #define PG8_STAGE(bufoff, gbase) do { _Pragma("unroll") for (int _i = 0; _i < 2; ++_i) \
;         __builtin_amdgcn_global_load_lds((const unsigned*)((const char*)(gbase) + voffA[_i]), (LAS unsigned*)(lds + (bufoff) + ldsw + _i * 8192), 16, 0, 0); } while (0)
; #define PG8_LDA(dst, b, h) do { _Pragma("unroll") for (int m = 0; m < 4; ++m) _Pragma("unroll") for (int k = 0; k < 2; ++k) dst[m][k] = *(const LAS h16x8*)(lds + PG8_SA(b, h) + aoff + m * 2048 + k * 1024); } while (0)
; #define PG8_LDB(dst, b, h) do { _Pragma("unroll") for (int n = 0; n < 2; ++n) _Pragma("unroll") for (int k = 0; k < 2; ++k) dst[n][k] = *(const LAS h16x8*)(lds + PG8_SB(b, h) + boff + n * 2048 + k * 1024); } while (0)
; #define PG8_LDA1(dst, b) do { if constexpr (!HALFM) PG8_LDA(dst, b, 1); } while (0)
; #define PG8_MMA1(At, B0, B1) do { if constexpr (!HALFM) { PG8_MMA(1, 0, At, B0); PG8_MMA(1, 1, At, B1); } } while (0)
; #define PG8_WAIT_V(n) asm volatile("s_waitcnt vmcnt(" #n ")" ::: "memory")
; #define PG8_WAIT_L(n) asm volatile("s_waitcnt lgkmcnt(" #n ")" ::: "memory")
; #define PG8_BAR __builtin_amdgcn_s_barrier()
; #define PG8_SCHED __builtin_amdgcn_sched_barrier(0)
; template <class Epi, bool ALIGN_EPI, bool SP2, bool BF = false, bool HALFM = false, class Order = StaticOrder>
; __device__ __forceinline__ void gemm_phase(LAS unsigned char* lds, const int tid, const Gemm g, const Order& S, const Epi& E, const bool dry = false) {
;     ...
;             PG8_LDB(B0, 0, 0); PG8_LDB(B1, 0, 1); PG8_SCHED; PG8_LDA(At, 0, 0); PG8_STAGE(PG8_SA(1, 1), a1 + hstep);
;             PG8_WAIT_V(8); PG8_WAIT_L(0); PG8_BAR; PG8_MMA(0, 0, At, B0); PG8_MMA(0, 1, At, B1); PG8_BAR; PG8_SCHED;
;             PG8_LDA1(At, 0); PG8_STAGE(PG8_SB(0, 0), b2); PG8_STAGE(PG8_SB(0, 1), b2 + hstep); PG8_STAGE(PG8_SA(0, 0), a2);
;             PG8_WAIT_V(8); PG8_WAIT_L(0); PG8_BAR; PG8_MMA1(At, B0, B1); PG8_BAR; PG8_SCHED;
;             PG8_LDB(B0, 1, 0); PG8_LDB(B1, 1, 1); PG8_SCHED; PG8_LDA(At, 1, 0); PG8_STAGE(PG8_SA(0, 1), a2 + hstep);
;             PG8_WAIT_V(8); PG8_WAIT_L(0); PG8_BAR; PG8_MMA(0, 0, At, B0); PG8_MMA(0, 1, At, B1); PG8_BAR; PG8_SCHED;
;             PG8_LDA1(At, 1); PG8_STAGE(PG8_SB(1, 0), b3); PG8_STAGE(PG8_SB(1, 1), b3 + hstep); PG8_STAGE(PG8_SA(1, 0), a3);
;             PG8_WAIT_V(8); PG8_WAIT_L(0); PG8_BAR; PG8_MMA1(At, B0, B1); PG8_BAR; PG8_SCHED;
	v_add_u32_e32 v144, s79, v198
	v_add_u32_e32 v160, s84, v198
	ds_read_b128 v[132:135], v144
	ds_read_b128 v[136:139], v144 offset:1024
	ds_read_b128 v[140:143], v144 offset:2048
	ds_read_b128 v[144:147], v144 offset:3072
	ds_read_b128 v[148:151], v160
	ds_read_b128 v[152:155], v160 offset:1024
	ds_read_b128 v[156:159], v160 offset:2048
	ds_read_b128 v[160:163], v160 offset:3072
	s_add_u32 s42, s42, 0x40000
	s_addc_u32 s43, s43, 0
	s_mov_b32 m0, s54
	s_nop 0
	ds_read_b128 v[170:173], v199 offset:32768
	ds_read_b128 v[174:177], v199 offset:33792
	ds_read_b128 v[178:181], v199 offset:34816
	ds_read_b128 v[182:185], v199 offset:35840
	ds_read_b128 v[186:189], v199 offset:36864
	ds_read_b128 v[190:193], v199 offset:37888
	ds_read_b128 v[200:203], v199 offset:38912
	ds_read_b128 v[204:207], v199 offset:39936
	global_load_lds_dwordx4 v0, s[42:43]
	s_nop 0
	s_mov_b32 m0, s55
	s_nop 0
	global_load_lds_dwordx4 v164, s[42:43]
	s_waitcnt vmcnt(8)
	s_waitcnt lgkmcnt(0)
	s_barrier
	s_waitcnt lgkmcnt(0)
	v_mfma_f32_16x16x32_f16 v[70:73], v[132:135], v[170:173], v[70:73]
	v_mfma_f32_16x16x32_f16 v[66:69], v[140:143], v[170:173], v[66:69]
	v_mfma_f32_16x16x32_f16 v[50:53], v[132:135], v[178:181], v[50:53]
	v_mfma_f32_16x16x32_f16 v[46:49], v[140:143], v[178:181], v[46:49]
	v_mfma_f32_16x16x32_f16 v[54:57], v[132:135], v[186:189], v[54:57]
	v_mfma_f32_16x16x32_f16 v[42:45], v[140:143], v[186:189], v[42:45]
	v_mfma_f32_16x16x32_f16 v[38:41], v[132:135], v[200:203], v[38:41]
	v_mfma_f32_16x16x32_f16 v[34:37], v[140:143], v[200:203], v[34:37]
	v_mfma_f32_16x16x32_f16 v[70:73], v[136:139], v[174:177], v[70:73]
	v_mfma_f32_16x16x32_f16 v[66:69], v[144:147], v[174:177], v[66:69]
	v_mfma_f32_16x16x32_f16 v[50:53], v[136:139], v[182:185], v[50:53]
	v_mfma_f32_16x16x32_f16 v[46:49], v[144:147], v[182:185], v[46:49]
	v_mfma_f32_16x16x32_f16 v[54:57], v[136:139], v[190:193], v[54:57]
	v_mfma_f32_16x16x32_f16 v[42:45], v[144:147], v[190:193], v[42:45]
	v_mfma_f32_16x16x32_f16 v[38:41], v[136:139], v[204:207], v[38:41]
	v_mfma_f32_16x16x32_f16 v[34:37], v[144:147], v[204:207], v[34:37]
	v_mfma_f32_16x16x32_f16 v[126:129], v[148:151], v[170:173], v[126:129]
	v_mfma_f32_16x16x32_f16 v[122:125], v[156:159], v[170:173], v[122:125]
	v_mfma_f32_16x16x32_f16 v[118:121], v[148:151], v[178:181], v[118:121]
	v_mfma_f32_16x16x32_f16 v[114:117], v[156:159], v[178:181], v[114:117]
	v_mfma_f32_16x16x32_f16 v[110:113], v[148:151], v[186:189], v[110:113]
	v_mfma_f32_16x16x32_f16 v[106:109], v[156:159], v[186:189], v[106:109]
	v_mfma_f32_16x16x32_f16 v[102:105], v[148:151], v[200:203], v[102:105]
	v_mfma_f32_16x16x32_f16 v[98:101], v[156:159], v[200:203], v[98:101]
	v_mfma_f32_16x16x32_f16 v[126:129], v[152:155], v[174:177], v[126:129]
	v_mfma_f32_16x16x32_f16 v[122:125], v[160:163], v[174:177], v[122:125]
	v_mfma_f32_16x16x32_f16 v[118:121], v[152:155], v[182:185], v[118:121]
	v_mfma_f32_16x16x32_f16 v[114:117], v[160:163], v[182:185], v[114:117]
	v_mfma_f32_16x16x32_f16 v[110:113], v[152:155], v[190:193], v[110:113]
	v_mfma_f32_16x16x32_f16 v[106:109], v[160:163], v[190:193], v[106:109]
	v_mfma_f32_16x16x32_f16 v[102:105], v[152:155], v[204:207], v[102:105]
	v_mfma_f32_16x16x32_f16 v[98:101], v[160:163], v[204:207], v[98:101]
	s_barrier
.Lin_seg4:
	s_mov_b32 m0, s80
	s_add_u32 vcc_lo, s38, 0x80
	s_addc_u32 vcc_hi, s39, 0
	s_add_u32 s38, s38, 0x40080
	ds_read_b128 v[170:173], v199 offset:49152
	ds_read_b128 v[174:177], v199 offset:50176
	ds_read_b128 v[178:181], v199 offset:51200
	ds_read_b128 v[182:185], v199 offset:52224
	ds_read_b128 v[186:189], v199 offset:53248
	ds_read_b128 v[190:193], v199 offset:54272
	ds_read_b128 v[200:203], v199 offset:55296
	ds_read_b128 v[204:207], v199 offset:56320
	global_load_lds_dwordx4 v0, vcc
	s_nop 0
	s_mov_b32 m0, s81
	s_addc_u32 s39, s39, 0
	global_load_lds_dwordx4 v164, vcc
	s_nop 0
	s_mov_b32 m0, s85
	s_nop 0
	global_load_lds_dwordx4 v0, s[38:39]
	s_nop 0
	s_mov_b32 m0, s86
	s_nop 0
	global_load_lds_dwordx4 v164, s[38:39]
	s_add_u32 vcc_lo, s42, 0xfffc0080
	s_addc_u32 vcc_hi, s43, -1
	s_mov_b32 m0, s82
	s_nop 0
	global_load_lds_dwordx4 v0, vcc
	s_nop 0
	s_mov_b32 m0, s83
	s_nop 0
	global_load_lds_dwordx4 v164, vcc
	s_waitcnt vmcnt(8)
	s_waitcnt lgkmcnt(0)
	s_barrier
	s_waitcnt lgkmcnt(0)
	v_mfma_f32_16x16x32_f16 v[30:33], v[132:135], v[170:173], v[30:33]
	v_mfma_f32_16x16x32_f16 v[26:29], v[140:143], v[170:173], v[26:29]
	v_mfma_f32_16x16x32_f16 v[22:25], v[132:135], v[178:181], v[22:25]
	v_mfma_f32_16x16x32_f16 v[18:21], v[140:143], v[178:181], v[18:21]
	v_mfma_f32_16x16x32_f16 v[14:17], v[132:135], v[186:189], v[14:17]
	v_mfma_f32_16x16x32_f16 v[10:13], v[140:143], v[186:189], v[10:13]
	v_mfma_f32_16x16x32_f16 v[6:9], v[132:135], v[200:203], v[6:9]
	v_mfma_f32_16x16x32_f16 v[2:5], v[140:143], v[200:203], v[2:5]
	v_mfma_f32_16x16x32_f16 v[30:33], v[136:139], v[174:177], v[30:33]
	v_mfma_f32_16x16x32_f16 v[26:29], v[144:147], v[174:177], v[26:29]
	v_mfma_f32_16x16x32_f16 v[22:25], v[136:139], v[182:185], v[22:25]
	v_mfma_f32_16x16x32_f16 v[18:21], v[144:147], v[182:185], v[18:21]
	v_mfma_f32_16x16x32_f16 v[14:17], v[136:139], v[190:193], v[14:17]
	v_mfma_f32_16x16x32_f16 v[10:13], v[144:147], v[190:193], v[10:13]
	v_mfma_f32_16x16x32_f16 v[6:9], v[136:139], v[204:207], v[6:9]
	v_mfma_f32_16x16x32_f16 v[2:5], v[144:147], v[204:207], v[2:5]
	v_mfma_f32_16x16x32_f16 v[94:97], v[148:151], v[170:173], v[94:97]
	v_mfma_f32_16x16x32_f16 v[90:93], v[156:159], v[170:173], v[90:93]
	v_mfma_f32_16x16x32_f16 v[86:89], v[148:151], v[178:181], v[86:89]
	v_mfma_f32_16x16x32_f16 v[82:85], v[156:159], v[178:181], v[82:85]
	v_mfma_f32_16x16x32_f16 v[78:81], v[148:151], v[186:189], v[78:81]
	v_mfma_f32_16x16x32_f16 v[74:77], v[156:159], v[186:189], v[74:77]
	v_mfma_f32_16x16x32_f16 v[62:65], v[148:151], v[200:203], v[62:65]
	v_mfma_f32_16x16x32_f16 v[58:61], v[156:159], v[200:203], v[58:61]
	v_mfma_f32_16x16x32_f16 v[94:97], v[152:155], v[174:177], v[94:97]
	v_mfma_f32_16x16x32_f16 v[90:93], v[160:163], v[174:177], v[90:93]
	v_mfma_f32_16x16x32_f16 v[86:89], v[152:155], v[182:185], v[86:89]
	v_mfma_f32_16x16x32_f16 v[82:85], v[160:163], v[182:185], v[82:85]
	v_mfma_f32_16x16x32_f16 v[78:81], v[152:155], v[190:193], v[78:81]
	v_mfma_f32_16x16x32_f16 v[74:77], v[160:163], v[190:193], v[74:77]
	v_mfma_f32_16x16x32_f16 v[62:65], v[152:155], v[204:207], v[62:65]
	v_mfma_f32_16x16x32_f16 v[58:61], v[160:163], v[204:207], v[58:61]
	s_barrier
	s_add_i32 s21, s21, 2
	s_add_u32 s11, s11, 0x100
	s_addc_u32 s19, s19, 0
	s_add_u32 s36, s36, 0x100
	s_addc_u32 s37, s37, 0
	s_cmp_gt_u32 s21, 13
	s_cbranch_scc0 .LBB0_561
	s_and_b64 vcc, exec, s[12:13]
	s_cbranch_vccz .LBB0_564
	s_barrier
